# phase-10 next-tile rstd: reduction rewritten with two batched cross-lane steps (2 LDS waits instead of 8), no denormal rescale (argument >= eps); on v074
# speedup vs baseline: 1.0020x; 1.0020x over previous
.LBB0_1093:
	ds_read_b128 v[146:149], v167
	ds_read_b128 v[150:153], v167 offset:1024
	ds_read_b128 v[178:181], v167 offset:2048
	ds_read_b128 v[182:185], v167 offset:3072
	s_add_u32 s28, s0, 0xfffc0080
	s_addc_u32 s29, s1, -1
	s_cmp_eq_u32 s64, 12
	s_cselect_b32 s45, s37, s29
	s_cselect_b32 s44, s60, s28
	s_cselect_b32 s43, s13, s63
	s_cselect_b32 s42, s61, s62
	v_lshl_add_u64 v[156:157], s[0:1], 0, v[138:139]
	s_add_i32 m0, s47, 0xc000
	ds_read_b128 v[186:189], v171
	ds_read_b128 v[196:199], v171 offset:1024
	ds_read_b128 v[200:203], v171 offset:2048
	ds_read_b128 v[204:207], v171 offset:3072
	ds_read_b128 v[208:211], v171 offset:4096
	ds_read_b128 v[212:215], v171 offset:5120
	ds_read_b128 v[216:219], v171 offset:6144
	ds_read_b128 v[220:223], v171 offset:7168
	global_load_lds_dwordx4 v[156:157], off
	v_lshl_add_u64 v[156:157], s[0:1], 0, v[140:141]
	s_add_i32 m0, s47, 0xe000
	s_nop 0
	global_load_lds_dwordx4 v[156:157], off
	s_waitcnt lgkmcnt(8)
	s_barrier
	s_waitcnt lgkmcnt(0)
	s_setprio 1
	s_waitcnt lgkmcnt(0)
	v_mfma_f32_16x16x32_bf16 v[124:127], v[146:149], v[186:189], v[124:127]
	v_mfma_f32_16x16x32_bf16 v[120:123], v[178:181], v[186:189], v[120:123]
	v_mfma_f32_16x16x32_bf16 v[108:111], v[146:149], v[200:203], v[108:111]
	v_mfma_f32_16x16x32_bf16 v[104:107], v[178:181], v[200:203], v[104:107]
	v_mfma_f32_16x16x32_bf16 v[92:95], v[146:149], v[208:211], v[92:95]
	v_mfma_f32_16x16x32_bf16 v[88:91], v[178:181], v[208:211], v[88:91]
	v_mfma_f32_16x16x32_bf16 v[76:79], v[146:149], v[216:219], v[76:79]
	v_mfma_f32_16x16x32_bf16 v[72:75], v[178:181], v[216:219], v[72:75]
	v_mfma_f32_16x16x32_bf16 v[124:127], v[150:153], v[196:199], v[124:127]
	v_mfma_f32_16x16x32_bf16 v[120:123], v[182:185], v[196:199], v[120:123]
	v_mfma_f32_16x16x32_bf16 v[108:111], v[150:153], v[204:207], v[108:111]
	v_mfma_f32_16x16x32_bf16 v[104:107], v[182:185], v[204:207], v[104:107]
	v_mfma_f32_16x16x32_bf16 v[92:95], v[150:153], v[212:215], v[92:95]
	v_mfma_f32_16x16x32_bf16 v[88:91], v[182:185], v[212:215], v[88:91]
	v_mfma_f32_16x16x32_bf16 v[76:79], v[150:153], v[220:223], v[76:79]
	v_mfma_f32_16x16x32_bf16 v[72:75], v[182:185], v[220:223], v[72:75]
	s_setprio 0
	s_barrier
	s_add_i32 s28, s56, s11
	v_lshl_add_u64 v[156:157], s[42:43], 0, v[132:133]
	s_mov_b32 m0, s28
	ds_read_b128 v[224:227], v175
	ds_read_b128 v[228:231], v175 offset:1024
	ds_read_b128 v[232:235], v175 offset:2048
	ds_read_b128 v[236:239], v175 offset:3072
	global_load_lds_dwordx4 v[156:157], off
	v_lshl_add_u64 v[160:161], s[42:43], 0, v[128:129]
	s_add_i32 m0, s28, 0x2000
	s_nop 0
	global_load_lds_dwordx4 v[160:161], off
	s_barrier
	s_waitcnt lgkmcnt(0)
	s_setprio 1
	s_waitcnt lgkmcnt(0)
	v_mfma_f32_16x16x32_bf16 v[116:119], v[224:227], v[186:189], v[116:119]
	v_mfma_f32_16x16x32_bf16 v[112:115], v[232:235], v[186:189], v[112:115]
	v_mfma_f32_16x16x32_bf16 v[100:103], v[224:227], v[200:203], v[100:103]
	v_mfma_f32_16x16x32_bf16 v[96:99], v[232:235], v[200:203], v[96:99]
	v_mfma_f32_16x16x32_bf16 v[84:87], v[224:227], v[208:211], v[84:87]
	v_mfma_f32_16x16x32_bf16 v[80:83], v[232:235], v[208:211], v[80:83]
	v_mfma_f32_16x16x32_bf16 v[68:71], v[224:227], v[216:219], v[68:71]
	v_mfma_f32_16x16x32_bf16 v[64:67], v[232:235], v[216:219], v[64:67]
	v_mfma_f32_16x16x32_bf16 v[116:119], v[228:231], v[196:199], v[116:119]
	v_mfma_f32_16x16x32_bf16 v[112:115], v[236:239], v[196:199], v[112:115]
	v_mfma_f32_16x16x32_bf16 v[100:103], v[228:231], v[204:207], v[100:103]
	v_mfma_f32_16x16x32_bf16 v[96:99], v[236:239], v[204:207], v[96:99]
	v_mfma_f32_16x16x32_bf16 v[84:87], v[228:231], v[212:215], v[84:87]
	v_mfma_f32_16x16x32_bf16 v[80:83], v[236:239], v[212:215], v[80:83]
	v_mfma_f32_16x16x32_bf16 v[68:71], v[228:231], v[220:223], v[68:71]
	v_mfma_f32_16x16x32_bf16 v[64:67], v[236:239], v[220:223], v[64:67]
	s_setprio 0
	s_mov_b32 m0, s47
	v_lshl_add_u64 v[164:165], s[44:45], 0, v[134:135]
	s_barrier
	ds_read_b128 v[186:189], v171 offset:16384
	ds_read_b128 v[196:199], v171 offset:17408
	ds_read_b128 v[200:203], v171 offset:18432
	ds_read_b128 v[204:207], v171 offset:19456
	ds_read_b128 v[208:211], v171 offset:20480
	ds_read_b128 v[212:215], v171 offset:21504
	ds_read_b128 v[216:219], v171 offset:22528
	ds_read_b128 v[220:223], v171 offset:23552
	global_load_lds_dwordx4 v[164:165], off
	v_lshl_add_u64 v[168:169], s[44:45], 0, v[130:131]
	s_mov_b32 m0, s48
	s_nop 0
	global_load_lds_dwordx4 v[168:169], off
	s_barrier
	s_waitcnt lgkmcnt(0)
	s_setprio 1
	s_waitcnt lgkmcnt(0)
	v_mfma_f32_16x16x32_bf16 v[60:63], v[146:149], v[186:189], v[60:63]
	v_mfma_f32_16x16x32_bf16 v[56:59], v[178:181], v[186:189], v[56:59]
	v_mfma_f32_16x16x32_bf16 v[44:47], v[146:149], v[200:203], v[44:47]
	v_mfma_f32_16x16x32_bf16 v[40:43], v[178:181], v[200:203], v[40:43]
	v_mfma_f32_16x16x32_bf16 v[28:31], v[146:149], v[208:211], v[28:31]
	v_mfma_f32_16x16x32_bf16 v[24:27], v[178:181], v[208:211], v[24:27]
	v_mfma_f32_16x16x32_bf16 v[12:15], v[146:149], v[216:219], v[12:15]
	v_mfma_f32_16x16x32_bf16 v[8:11], v[178:181], v[216:219], v[8:11]
	v_mfma_f32_16x16x32_bf16 v[60:63], v[150:153], v[196:199], v[60:63]
	v_mfma_f32_16x16x32_bf16 v[56:59], v[182:185], v[196:199], v[56:59]
	v_mfma_f32_16x16x32_bf16 v[44:47], v[150:153], v[204:207], v[44:47]
	v_mfma_f32_16x16x32_bf16 v[40:43], v[182:185], v[204:207], v[40:43]
	v_mfma_f32_16x16x32_bf16 v[28:31], v[150:153], v[212:215], v[28:31]
	v_mfma_f32_16x16x32_bf16 v[24:27], v[182:185], v[212:215], v[24:27]
	v_mfma_f32_16x16x32_bf16 v[12:15], v[150:153], v[220:223], v[12:15]
	v_mfma_f32_16x16x32_bf16 v[8:11], v[182:185], v[220:223], v[8:11]
	s_setprio 0
	s_barrier
	s_add_u32 s66, s42, 0x40000
	s_addc_u32 s67, s43, 0
	s_add_i32 s28, s57, s11
	v_lshl_add_u64 v[146:147], s[66:67], 0, v[132:133]
	s_mov_b32 m0, s28
	s_nop 0
	global_load_lds_dwordx4 v[146:147], off
	v_lshl_add_u64 v[146:147], s[66:67], 0, v[128:129]
	s_add_i32 m0, s28, 0x2000
	s_nop 0
	global_load_lds_dwordx4 v[146:147], off
	s_waitcnt vmcnt(6)
	s_barrier
	s_setprio 1
	v_mfma_f32_16x16x32_bf16 v[52:55], v[224:227], v[186:189], v[52:55]
	v_mfma_f32_16x16x32_bf16 v[48:51], v[232:235], v[186:189], v[48:51]
	v_mfma_f32_16x16x32_bf16 v[36:39], v[224:227], v[200:203], v[36:39]
	v_mfma_f32_16x16x32_bf16 v[32:35], v[232:235], v[200:203], v[32:35]
	v_mfma_f32_16x16x32_bf16 v[20:23], v[224:227], v[208:211], v[20:23]
	v_mfma_f32_16x16x32_bf16 v[16:19], v[232:235], v[208:211], v[16:19]
	v_mfma_f32_16x16x32_bf16 v[4:7], v[224:227], v[216:219], v[4:7]
	v_mfma_f32_16x16x32_bf16 v[0:3], v[232:235], v[216:219], v[0:3]
	v_mfma_f32_16x16x32_bf16 v[52:55], v[228:231], v[196:199], v[52:55]
	v_mfma_f32_16x16x32_bf16 v[48:51], v[236:239], v[196:199], v[48:51]
	v_mfma_f32_16x16x32_bf16 v[36:39], v[228:231], v[204:207], v[36:39]
	v_mfma_f32_16x16x32_bf16 v[32:35], v[236:239], v[204:207], v[32:35]
	v_mfma_f32_16x16x32_bf16 v[20:23], v[228:231], v[212:215], v[20:23]
	v_mfma_f32_16x16x32_bf16 v[16:19], v[236:239], v[212:215], v[16:19]
	v_mfma_f32_16x16x32_bf16 v[4:7], v[228:231], v[220:223], v[4:7]
	v_mfma_f32_16x16x32_bf16 v[0:3], v[236:239], v[220:223], v[0:3]
	s_setprio 0
	s_add_i32 s28, 0, 0x18000
	v_add_u32_e32 v154, s28, v159
	s_barrier
	ds_read_b128 v[146:149], v154
	ds_read_b128 v[150:153], v154 offset:1024
	ds_read_b128 v[178:181], v154 offset:2048
	ds_read_b128 v[182:185], v154 offset:3072
	s_add_u32 s44, s44, 0x40000
	s_addc_u32 s45, s45, 0
	s_mov_b32 m0, s49
	v_lshl_add_u64 v[172:173], s[44:45], 0, v[134:135]
	ds_read_b128 v[186:189], v171 offset:32768
	ds_read_b128 v[196:199], v171 offset:33792
	ds_read_b128 v[200:203], v171 offset:34816
	ds_read_b128 v[204:207], v171 offset:35840
	ds_read_b128 v[208:211], v171 offset:36864
	ds_read_b128 v[212:215], v171 offset:37888
	ds_read_b128 v[216:219], v171 offset:38912
	ds_read_b128 v[220:223], v171 offset:39936
	global_load_lds_dwordx4 v[172:173], off
	v_lshl_add_u64 v[172:173], s[44:45], 0, v[130:131]
	s_mov_b32 m0, s50
	s_nop 0
	global_load_lds_dwordx4 v[172:173], off
	s_waitcnt lgkmcnt(8)
	s_barrier
	s_waitcnt lgkmcnt(0)
	s_setprio 1
	s_waitcnt lgkmcnt(0)
	v_mfma_f32_16x16x32_bf16 v[124:127], v[146:149], v[186:189], v[124:127]
	v_mfma_f32_16x16x32_bf16 v[120:123], v[178:181], v[186:189], v[120:123]
	v_mfma_f32_16x16x32_bf16 v[108:111], v[146:149], v[200:203], v[108:111]
	v_mfma_f32_16x16x32_bf16 v[104:107], v[178:181], v[200:203], v[104:107]
	v_mfma_f32_16x16x32_bf16 v[92:95], v[146:149], v[208:211], v[92:95]
	v_mfma_f32_16x16x32_bf16 v[88:91], v[178:181], v[208:211], v[88:91]
	v_mfma_f32_16x16x32_bf16 v[76:79], v[146:149], v[216:219], v[76:79]
	v_mfma_f32_16x16x32_bf16 v[72:75], v[178:181], v[216:219], v[72:75]
	v_mfma_f32_16x16x32_bf16 v[124:127], v[150:153], v[196:199], v[124:127]
	v_mfma_f32_16x16x32_bf16 v[120:123], v[182:185], v[196:199], v[120:123]
	v_mfma_f32_16x16x32_bf16 v[108:111], v[150:153], v[204:207], v[108:111]
	v_mfma_f32_16x16x32_bf16 v[104:107], v[182:185], v[204:207], v[104:107]
	v_mfma_f32_16x16x32_bf16 v[92:95], v[150:153], v[212:215], v[92:95]
	v_mfma_f32_16x16x32_bf16 v[88:91], v[182:185], v[212:215], v[88:91]
	v_mfma_f32_16x16x32_bf16 v[76:79], v[150:153], v[220:223], v[76:79]
	v_mfma_f32_16x16x32_bf16 v[72:75], v[182:185], v[220:223], v[72:75]
	s_setprio 0
	s_barrier
	s_add_i32 s29, 0, 0x1c000
	s_add_i32 s28, s28, s11
	v_add_u32_e32 v154, s29, v159
	v_lshl_add_u64 v[156:157], v[156:157], 0, s[6:7]
	s_mov_b32 m0, s28
	ds_read_b128 v[224:227], v154
	ds_read_b128 v[228:231], v154 offset:1024
	ds_read_b128 v[232:235], v154 offset:2048
	ds_read_b128 v[236:239], v154 offset:3072
	global_load_lds_dwordx4 v[156:157], off
	v_lshl_add_u64 v[156:157], v[160:161], 0, s[6:7]
	s_add_i32 m0, s28, 0x2000
	s_nop 0
	global_load_lds_dwordx4 v[156:157], off
	s_barrier
	s_waitcnt lgkmcnt(0)
	s_setprio 1
	s_waitcnt lgkmcnt(0)
	v_mfma_f32_16x16x32_bf16 v[116:119], v[224:227], v[186:189], v[116:119]
	v_mfma_f32_16x16x32_bf16 v[112:115], v[232:235], v[186:189], v[112:115]
	v_mfma_f32_16x16x32_bf16 v[100:103], v[224:227], v[200:203], v[100:103]
	v_mfma_f32_16x16x32_bf16 v[96:99], v[232:235], v[200:203], v[96:99]
	v_mfma_f32_16x16x32_bf16 v[84:87], v[224:227], v[208:211], v[84:87]
	v_mfma_f32_16x16x32_bf16 v[80:83], v[232:235], v[208:211], v[80:83]
	v_mfma_f32_16x16x32_bf16 v[68:71], v[224:227], v[216:219], v[68:71]
	v_mfma_f32_16x16x32_bf16 v[64:67], v[232:235], v[216:219], v[64:67]
	v_mfma_f32_16x16x32_bf16 v[116:119], v[228:231], v[196:199], v[116:119]
	v_mfma_f32_16x16x32_bf16 v[112:115], v[236:239], v[196:199], v[112:115]
	v_mfma_f32_16x16x32_bf16 v[100:103], v[228:231], v[204:207], v[100:103]
	v_mfma_f32_16x16x32_bf16 v[96:99], v[236:239], v[204:207], v[96:99]
	v_mfma_f32_16x16x32_bf16 v[84:87], v[228:231], v[212:215], v[84:87]
	v_mfma_f32_16x16x32_bf16 v[80:83], v[236:239], v[212:215], v[80:83]
	v_mfma_f32_16x16x32_bf16 v[68:71], v[228:231], v[220:223], v[68:71]
	v_mfma_f32_16x16x32_bf16 v[64:67], v[236:239], v[220:223], v[64:67]
	s_setprio 0
	s_mov_b32 m0, s53
	v_lshl_add_u64 v[156:157], v[164:165], 0, s[6:7]
	s_barrier
	ds_read_b128 v[186:189], v171 offset:49152
	ds_read_b128 v[196:199], v171 offset:50176
	ds_read_b128 v[200:203], v171 offset:51200
	ds_read_b128 v[204:207], v171 offset:52224
	ds_read_b128 v[208:211], v171 offset:53248
	ds_read_b128 v[212:215], v171 offset:54272
	ds_read_b128 v[216:219], v171 offset:55296
	ds_read_b128 v[220:223], v171 offset:56320
	global_load_lds_dwordx4 v[156:157], off
	v_lshl_add_u64 v[156:157], v[168:169], 0, s[6:7]
	s_mov_b32 m0, s54
	s_nop 0
	global_load_lds_dwordx4 v[156:157], off
	s_barrier
	s_waitcnt lgkmcnt(0)
	s_setprio 1
	s_waitcnt lgkmcnt(0)
	v_mfma_f32_16x16x32_bf16 v[60:63], v[146:149], v[186:189], v[60:63]
	v_mfma_f32_16x16x32_bf16 v[56:59], v[178:181], v[186:189], v[56:59]
	v_mfma_f32_16x16x32_bf16 v[44:47], v[146:149], v[200:203], v[44:47]
	v_mfma_f32_16x16x32_bf16 v[40:43], v[178:181], v[200:203], v[40:43]
	v_mfma_f32_16x16x32_bf16 v[28:31], v[146:149], v[208:211], v[28:31]
	v_mfma_f32_16x16x32_bf16 v[24:27], v[178:181], v[208:211], v[24:27]
	v_mfma_f32_16x16x32_bf16 v[12:15], v[146:149], v[216:219], v[12:15]
	v_mfma_f32_16x16x32_bf16 v[8:11], v[178:181], v[216:219], v[8:11]
	v_mfma_f32_16x16x32_bf16 v[60:63], v[150:153], v[196:199], v[60:63]
	v_mfma_f32_16x16x32_bf16 v[56:59], v[182:185], v[196:199], v[56:59]
	v_mfma_f32_16x16x32_bf16 v[44:47], v[150:153], v[204:207], v[44:47]
	v_mfma_f32_16x16x32_bf16 v[40:43], v[182:185], v[204:207], v[40:43]
	v_mfma_f32_16x16x32_bf16 v[28:31], v[150:153], v[212:215], v[28:31]
	v_mfma_f32_16x16x32_bf16 v[24:27], v[182:185], v[212:215], v[24:27]
	v_mfma_f32_16x16x32_bf16 v[12:15], v[150:153], v[220:223], v[12:15]
	v_mfma_f32_16x16x32_bf16 v[8:11], v[182:185], v[220:223], v[8:11]
	s_setprio 0
	s_barrier
	s_add_u32 s42, s42, 0x40080
	s_addc_u32 s43, s43, 0
	s_add_i32 s28, s29, s11
	v_lshl_add_u64 v[146:147], s[42:43], 0, v[132:133]
	s_mov_b32 m0, s28
	s_nop 0
	global_load_lds_dwordx4 v[146:147], off
	v_lshl_add_u64 v[146:147], s[42:43], 0, v[128:129]
	s_add_i32 m0, s28, 0x2000
	s_nop 0
	global_load_lds_dwordx4 v[146:147], off
	s_waitcnt vmcnt(6)
	s_barrier
	s_setprio 1
	v_mfma_f32_16x16x32_bf16 v[52:55], v[224:227], v[186:189], v[52:55]
	v_mfma_f32_16x16x32_bf16 v[48:51], v[232:235], v[186:189], v[48:51]
	v_mfma_f32_16x16x32_bf16 v[36:39], v[224:227], v[200:203], v[36:39]
	v_mfma_f32_16x16x32_bf16 v[32:35], v[232:235], v[200:203], v[32:35]
	v_mfma_f32_16x16x32_bf16 v[20:23], v[224:227], v[208:211], v[20:23]
	v_mfma_f32_16x16x32_bf16 v[16:19], v[232:235], v[208:211], v[16:19]
	v_mfma_f32_16x16x32_bf16 v[4:7], v[224:227], v[216:219], v[4:7]
	v_mfma_f32_16x16x32_bf16 v[0:3], v[232:235], v[216:219], v[0:3]
	v_mfma_f32_16x16x32_bf16 v[52:55], v[228:231], v[196:199], v[52:55]
	v_mfma_f32_16x16x32_bf16 v[48:51], v[236:239], v[196:199], v[48:51]
	v_mfma_f32_16x16x32_bf16 v[36:39], v[228:231], v[204:207], v[36:39]
	v_mfma_f32_16x16x32_bf16 v[32:35], v[236:239], v[204:207], v[32:35]
	v_mfma_f32_16x16x32_bf16 v[20:23], v[228:231], v[212:215], v[20:23]
	v_mfma_f32_16x16x32_bf16 v[16:19], v[236:239], v[212:215], v[16:19]
	v_mfma_f32_16x16x32_bf16 v[4:7], v[228:231], v[220:223], v[4:7]
	v_mfma_f32_16x16x32_bf16 v[0:3], v[236:239], v[220:223], v[0:3]
	s_setprio 0
	s_add_i32 s64, s64, 2
	s_add_u32 s0, s0, 0x100
	s_addc_u32 s1, s1, 0
	s_add_u32 s62, s62, 0x100
	s_addc_u32 s63, s63, 0
	s_cmp_gt_u32 s64, 13
	s_barrier
	s_cbranch_scc0 .LBB0_1093
	v_lshl_add_u32 v168, s4, 8, v155
	v_or_b32_e32 v164, 16, v168
	v_or_b32_e32 v160, 32, v168
	v_or_b32_e32 v156, 48, v168
	v_add_u32_e32 v152, 0x80, v168
	v_add_u32_e32 v150, 0x90, v168
	v_add_u32_e32 v148, 0xa0, v168
	v_add_u32_e32 v146, 0xb0, v168
	v_lshl_or_b32 v172, s5, 7, v163
	v_mov_b32_e32 v178, v240
	v_mov_b32_e32 v179, v240
	v_mov_b32_e32 v154, v241
	s_and_b32 s0, s36, 0x7f
	v_lshl_add_u32 v228, s0, 8, v155
	v_mov_b32_e32 v229, 0
	v_lshlrev_b32_e32 v228, 6, v228
	v_lshl_add_u64 v[230:231], v[136:137], 0, v[228:229]
	v_mov_b32_e32 v228, 0x2000
	v_lshl_add_u64 v[232:233], v[230:231], 0, v[228:229]
	global_load_dwordx4 v[216:219], v[230:231], off
	global_load_dwordx4 v[220:223], v[230:231], off offset:1024
	global_load_dwordx4 v[224:227], v[230:231], off offset:2048
	global_load_dwordx4 v[196:199], v[230:231], off offset:3072
	global_load_dwordx4 v[200:203], v[232:233], off
	global_load_dwordx4 v[204:207], v[232:233], off offset:1024
	global_load_dwordx4 v[208:211], v[232:233], off offset:2048
	global_load_dwordx4 v[212:215], v[232:233], off offset:3072
	v_pk_mul_f32 v[124:125], v[124:125], v[178:179] op_sel_hi:[1,0]
	v_pk_mul_f32 v[126:127], v[126:127], v[178:179] op_sel_hi:[1,0]
	v_mul_f32_e32 v147, 0xbfb8aa3b, v124
	v_exp_f32_e32 v147, v147
	v_mul_f32_e32 v149, 0xbfb8aa3b, v125
	v_exp_f32_e32 v149, v149
	v_mul_f32_e32 v151, 0xbfb8aa3b, v127
	v_add_f32_e32 v147, 1.0, v147
	v_rcp_f32_e32 v180, v147
	v_add_f32_e32 v147, 1.0, v149
	v_mul_f32_e32 v149, 0xbfb8aa3b, v126
	v_exp_f32_e32 v149, v149
	v_exp_f32_e32 v151, v151
	v_rcp_f32_e32 v181, v147
	v_pk_mul_f32 v[116:117], v[116:117], v[178:179] op_sel_hi:[1,0]
	v_add_f32_e32 v147, 1.0, v149
	v_rcp_f32_e32 v182, v147
	v_add_f32_e32 v147, 1.0, v151
	v_rcp_f32_e32 v183, v147
	v_pk_mul_f32 v[124:125], v[124:125], v[180:181]
	v_pk_mul_f32 v[120:121], v[120:121], v[178:179] op_sel_hi:[1,0]
	v_pk_mul_f32 v[116:117], v[116:117], v[124:125]
	v_pk_mul_f32 v[124:125], v[126:127], v[182:183]
	v_mul_f32_e32 v126, 0xbfb8aa3b, v120
	v_exp_f32_e32 v126, v126
	v_pk_mul_f32 v[118:119], v[118:119], v[178:179] op_sel_hi:[1,0]
	v_pk_mul_f32 v[122:123], v[122:123], v[178:179] op_sel_hi:[1,0]
	v_pk_mul_f32 v[118:119], v[118:119], v[124:125]
	v_mul_f32_e32 v124, 0xbfb8aa3b, v121
	v_exp_f32_e32 v125, v124
	v_add_f32_e32 v124, 1.0, v126
	v_mul_f32_e32 v126, 0xbfb8aa3b, v122
	v_mul_f32_e32 v127, 0xbfb8aa3b, v123
	v_exp_f32_e32 v126, v126
	v_exp_f32_e32 v127, v127
	v_add_f32_e32 v125, 1.0, v125
	v_rcp_f32_e32 v124, v124
	v_rcp_f32_e32 v125, v125
	v_add_f32_e32 v126, 1.0, v126
	v_add_f32_e32 v127, 1.0, v127
	v_rcp_f32_e32 v126, v126
	v_rcp_f32_e32 v127, v127
	v_pk_mul_f32 v[112:113], v[112:113], v[178:179] op_sel_hi:[1,0]
	v_pk_mul_f32 v[120:121], v[120:121], v[124:125]
	v_pk_mul_f32 v[114:115], v[114:115], v[178:179] op_sel_hi:[1,0]
	v_pk_mul_f32 v[112:113], v[112:113], v[120:121]
	v_pk_mul_f32 v[120:121], v[122:123], v[126:127]
	v_ashrrev_i32_e32 v173, 31, v172
	v_pk_mul_f32 v[114:115], v[114:115], v[120:121]
	v_cvt_pk_bf16_f32 v116, v116, v117
	v_cvt_pk_bf16_f32 v117, v118, v119
	v_cvt_pk_bf16_f32 v118, v112, v113
	v_mov_b64_e32 v[112:113], s[20:21]
	v_cvt_pk_bf16_f32 v119, v114, v115
	v_mad_i64_i32 v[120:121], s[0:1], v168, s59, v[112:113]
	v_lshlrev_b64 v[114:115], 1, v[172:173]
	v_lshl_add_u64 v[120:121], v[120:121], 0, v[114:115]
	v_pk_mul_f32 v[108:109], v[108:109], v[176:177] op_sel_hi:[1,0]
	global_store_dwordx4 v[120:121], v[116:119], off
	v_mul_f32_e32 v122, 0xbfb8aa3b, v108
	v_pk_mul_f32 v[110:111], v[110:111], v[176:177] op_sel_hi:[1,0]
	v_mul_f32_e32 v116, 0xbfb8aa3b, v109
	v_exp_f32_e32 v122, v122
	v_exp_f32_e32 v117, v116
	v_mul_f32_e32 v118, 0xbfb8aa3b, v110
	v_mul_f32_e32 v119, 0xbfb8aa3b, v111
	v_exp_f32_e32 v118, v118
	v_exp_f32_e32 v119, v119
	v_add_f32_e32 v116, 1.0, v122
	v_add_f32_e32 v117, 1.0, v117
	v_rcp_f32_e32 v116, v116
	v_rcp_f32_e32 v117, v117
	v_add_f32_e32 v118, 1.0, v118
	v_add_f32_e32 v119, 1.0, v119
	v_rcp_f32_e32 v118, v118
	v_rcp_f32_e32 v119, v119
	v_pk_mul_f32 v[100:101], v[100:101], v[176:177] op_sel_hi:[1,0]
	v_pk_mul_f32 v[108:109], v[108:109], v[116:117]
	v_pk_mul_f32 v[104:105], v[104:105], v[176:177] op_sel_hi:[1,0]
	v_pk_mul_f32 v[100:101], v[100:101], v[108:109]
	v_pk_mul_f32 v[108:109], v[110:111], v[118:119]
	v_mul_f32_e32 v110, 0xbfb8aa3b, v104
	v_exp_f32_e32 v110, v110
	v_pk_mul_f32 v[102:103], v[102:103], v[176:177] op_sel_hi:[1,0]
	v_pk_mul_f32 v[106:107], v[106:107], v[176:177] op_sel_hi:[1,0]
	v_pk_mul_f32 v[102:103], v[102:103], v[108:109]
	v_mul_f32_e32 v108, 0xbfb8aa3b, v105
	v_exp_f32_e32 v109, v108
	v_add_f32_e32 v108, 1.0, v110
	v_mul_f32_e32 v110, 0xbfb8aa3b, v106
	v_mul_f32_e32 v111, 0xbfb8aa3b, v107
	v_exp_f32_e32 v110, v110
	v_exp_f32_e32 v111, v111
	v_add_f32_e32 v109, 1.0, v109
	v_rcp_f32_e32 v108, v108
	v_rcp_f32_e32 v109, v109
	v_add_f32_e32 v110, 1.0, v110
	v_add_f32_e32 v111, 1.0, v111
	v_rcp_f32_e32 v110, v110
	v_rcp_f32_e32 v111, v111
	v_pk_mul_f32 v[96:97], v[96:97], v[176:177] op_sel_hi:[1,0]
	v_pk_mul_f32 v[104:105], v[104:105], v[108:109]
	v_pk_mul_f32 v[92:93], v[92:93], v[174:175] op_sel_hi:[1,0]
	v_pk_mul_f32 v[104:105], v[96:97], v[104:105]
	v_pk_mul_f32 v[96:97], v[98:99], v[176:177] op_sel_hi:[1,0]
	v_pk_mul_f32 v[98:99], v[106:107], v[110:111]
	v_pk_mul_f32 v[94:95], v[94:95], v[174:175] op_sel_hi:[1,0]
	v_pk_mul_f32 v[106:107], v[96:97], v[98:99]
	v_cvt_pk_bf16_f32 v96, v100, v101
	v_mad_i64_i32 v[100:101], s[0:1], v164, s59, v[112:113]
	v_cvt_pk_bf16_f32 v97, v102, v103
	v_cvt_pk_bf16_f32 v98, v104, v105
	v_cvt_pk_bf16_f32 v99, v106, v107
	v_lshl_add_u64 v[100:101], v[100:101], 0, v[114:115]
	v_mul_f32_e32 v102, 0xbfb8aa3b, v92
	global_store_dwordx4 v[100:101], v[96:99], off
	v_exp_f32_e32 v102, v102
	v_pk_mul_f32 v[84:85], v[84:85], v[174:175] op_sel_hi:[1,0]
	v_mul_f32_e32 v96, 0xbfb8aa3b, v93
	v_exp_f32_e32 v97, v96
	v_mul_f32_e32 v98, 0xbfb8aa3b, v94
	v_mul_f32_e32 v99, 0xbfb8aa3b, v95
	v_exp_f32_e32 v98, v98
	v_exp_f32_e32 v99, v99
	v_add_f32_e32 v96, 1.0, v102
	v_add_f32_e32 v97, 1.0, v97
	v_rcp_f32_e32 v96, v96
	v_rcp_f32_e32 v97, v97
	v_add_f32_e32 v98, 1.0, v98
	v_add_f32_e32 v99, 1.0, v99
	v_rcp_f32_e32 v98, v98
	v_rcp_f32_e32 v99, v99
	v_pk_mul_f32 v[92:93], v[92:93], v[96:97]
	v_pk_mul_f32 v[88:89], v[88:89], v[174:175] op_sel_hi:[1,0]
	v_pk_mul_f32 v[84:85], v[84:85], v[92:93]
	v_pk_mul_f32 v[92:93], v[94:95], v[98:99]
	v_mul_f32_e32 v94, 0xbfb8aa3b, v88
	v_exp_f32_e32 v94, v94
	v_pk_mul_f32 v[86:87], v[86:87], v[174:175] op_sel_hi:[1,0]
	v_pk_mul_f32 v[90:91], v[90:91], v[174:175] op_sel_hi:[1,0]
	v_pk_mul_f32 v[86:87], v[86:87], v[92:93]
	v_mul_f32_e32 v92, 0xbfb8aa3b, v89
	v_exp_f32_e32 v93, v92
	v_add_f32_e32 v92, 1.0, v94
	v_mul_f32_e32 v94, 0xbfb8aa3b, v90
	v_mul_f32_e32 v95, 0xbfb8aa3b, v91
	v_exp_f32_e32 v94, v94
	v_exp_f32_e32 v95, v95
	v_add_f32_e32 v93, 1.0, v93
	v_rcp_f32_e32 v92, v92
	v_rcp_f32_e32 v93, v93
	v_add_f32_e32 v94, 1.0, v94
	v_add_f32_e32 v95, 1.0, v95
	v_rcp_f32_e32 v94, v94
	v_rcp_f32_e32 v95, v95
	v_pk_mul_f32 v[80:81], v[80:81], v[174:175] op_sel_hi:[1,0]
	v_pk_mul_f32 v[88:89], v[88:89], v[92:93]
	v_pk_mul_f32 v[76:77], v[76:77], v[170:171] op_sel_hi:[1,0]
	v_pk_mul_f32 v[88:89], v[80:81], v[88:89]
	v_pk_mul_f32 v[80:81], v[82:83], v[174:175] op_sel_hi:[1,0]
	v_pk_mul_f32 v[82:83], v[90:91], v[94:95]
	v_pk_mul_f32 v[78:79], v[78:79], v[170:171] op_sel_hi:[1,0]
	v_pk_mul_f32 v[90:91], v[80:81], v[82:83]
	v_cvt_pk_bf16_f32 v80, v84, v85
	v_mad_i64_i32 v[84:85], s[0:1], v160, s59, v[112:113]
	v_cvt_pk_bf16_f32 v81, v86, v87
	v_cvt_pk_bf16_f32 v82, v88, v89
	v_cvt_pk_bf16_f32 v83, v90, v91
	v_lshl_add_u64 v[84:85], v[84:85], 0, v[114:115]
	v_mul_f32_e32 v86, 0xbfb8aa3b, v76
	global_store_dwordx4 v[84:85], v[80:83], off
	v_exp_f32_e32 v86, v86
	v_pk_mul_f32 v[68:69], v[68:69], v[170:171] op_sel_hi:[1,0]
	v_mul_f32_e32 v80, 0xbfb8aa3b, v77
	v_exp_f32_e32 v81, v80
	v_mul_f32_e32 v82, 0xbfb8aa3b, v78
	v_mul_f32_e32 v83, 0xbfb8aa3b, v79
	v_exp_f32_e32 v82, v82
	v_exp_f32_e32 v83, v83
	v_add_f32_e32 v80, 1.0, v86
	v_add_f32_e32 v81, 1.0, v81
	v_rcp_f32_e32 v80, v80
	v_rcp_f32_e32 v81, v81
	v_add_f32_e32 v82, 1.0, v82
	v_add_f32_e32 v83, 1.0, v83
	v_rcp_f32_e32 v82, v82
	v_rcp_f32_e32 v83, v83
	v_pk_mul_f32 v[76:77], v[76:77], v[80:81]
	v_pk_mul_f32 v[72:73], v[72:73], v[170:171] op_sel_hi:[1,0]
	v_pk_mul_f32 v[68:69], v[68:69], v[76:77]
	v_pk_mul_f32 v[76:77], v[78:79], v[82:83]
	v_mul_f32_e32 v78, 0xbfb8aa3b, v72
	v_exp_f32_e32 v78, v78
	v_pk_mul_f32 v[70:71], v[70:71], v[170:171] op_sel_hi:[1,0]
	v_pk_mul_f32 v[74:75], v[74:75], v[170:171] op_sel_hi:[1,0]
	v_pk_mul_f32 v[70:71], v[70:71], v[76:77]
	v_mul_f32_e32 v76, 0xbfb8aa3b, v73
	v_exp_f32_e32 v77, v76
	v_add_f32_e32 v76, 1.0, v78
	v_mul_f32_e32 v78, 0xbfb8aa3b, v74
	v_mul_f32_e32 v79, 0xbfb8aa3b, v75
	v_exp_f32_e32 v78, v78
	v_exp_f32_e32 v79, v79
	v_add_f32_e32 v77, 1.0, v77
	v_rcp_f32_e32 v76, v76
	v_rcp_f32_e32 v77, v77
	v_add_f32_e32 v78, 1.0, v78
	v_add_f32_e32 v79, 1.0, v79
	v_rcp_f32_e32 v78, v78
	v_rcp_f32_e32 v79, v79
	v_pk_mul_f32 v[64:65], v[64:65], v[170:171] op_sel_hi:[1,0]
	v_pk_mul_f32 v[72:73], v[72:73], v[76:77]
	v_pk_mul_f32 v[60:61], v[60:61], v[166:167] op_sel_hi:[1,0]
	v_pk_mul_f32 v[72:73], v[64:65], v[72:73]
	v_pk_mul_f32 v[64:65], v[66:67], v[170:171] op_sel_hi:[1,0]
	v_pk_mul_f32 v[66:67], v[74:75], v[78:79]
	v_pk_mul_f32 v[62:63], v[62:63], v[166:167] op_sel_hi:[1,0]
	v_pk_mul_f32 v[74:75], v[64:65], v[66:67]
	v_cvt_pk_bf16_f32 v64, v68, v69
	v_mad_i64_i32 v[68:69], s[0:1], v156, s59, v[112:113]
	v_cvt_pk_bf16_f32 v65, v70, v71
	v_cvt_pk_bf16_f32 v66, v72, v73
	v_cvt_pk_bf16_f32 v67, v74, v75
	v_lshl_add_u64 v[68:69], v[68:69], 0, v[114:115]
	v_mul_f32_e32 v70, 0xbfb8aa3b, v60
	global_store_dwordx4 v[68:69], v[64:67], off
	v_exp_f32_e32 v70, v70
	v_pk_mul_f32 v[52:53], v[52:53], v[166:167] op_sel_hi:[1,0]
	v_mul_f32_e32 v64, 0xbfb8aa3b, v61
	v_exp_f32_e32 v65, v64
	v_mul_f32_e32 v66, 0xbfb8aa3b, v62
	v_mul_f32_e32 v67, 0xbfb8aa3b, v63
	v_exp_f32_e32 v66, v66
	v_exp_f32_e32 v67, v67
	v_add_f32_e32 v64, 1.0, v70
	v_add_f32_e32 v65, 1.0, v65
	v_rcp_f32_e32 v64, v64
	v_rcp_f32_e32 v65, v65
	v_add_f32_e32 v66, 1.0, v66
	v_add_f32_e32 v67, 1.0, v67
	v_rcp_f32_e32 v66, v66
	v_rcp_f32_e32 v67, v67
	v_pk_mul_f32 v[60:61], v[60:61], v[64:65]
	v_pk_mul_f32 v[56:57], v[56:57], v[166:167] op_sel_hi:[1,0]
	v_pk_mul_f32 v[52:53], v[52:53], v[60:61]
	v_pk_mul_f32 v[60:61], v[62:63], v[66:67]
	v_mul_f32_e32 v62, 0xbfb8aa3b, v56
	v_exp_f32_e32 v62, v62
	v_pk_mul_f32 v[54:55], v[54:55], v[166:167] op_sel_hi:[1,0]
	v_pk_mul_f32 v[58:59], v[58:59], v[166:167] op_sel_hi:[1,0]
	v_pk_mul_f32 v[54:55], v[54:55], v[60:61]
	v_mul_f32_e32 v60, 0xbfb8aa3b, v57
	v_exp_f32_e32 v61, v60
	v_add_f32_e32 v60, 1.0, v62
	v_mul_f32_e32 v62, 0xbfb8aa3b, v58
	v_mul_f32_e32 v63, 0xbfb8aa3b, v59
	v_exp_f32_e32 v62, v62
	v_exp_f32_e32 v63, v63
	v_add_f32_e32 v61, 1.0, v61
	v_rcp_f32_e32 v60, v60
	v_rcp_f32_e32 v61, v61
	v_add_f32_e32 v62, 1.0, v62
	v_add_f32_e32 v63, 1.0, v63
	v_rcp_f32_e32 v62, v62
	v_rcp_f32_e32 v63, v63
	v_pk_mul_f32 v[48:49], v[48:49], v[166:167] op_sel_hi:[1,0]
	v_pk_mul_f32 v[56:57], v[56:57], v[60:61]
	v_pk_mul_f32 v[44:45], v[44:45], v[162:163] op_sel_hi:[1,0]
	v_pk_mul_f32 v[56:57], v[48:49], v[56:57]
	v_pk_mul_f32 v[48:49], v[50:51], v[166:167] op_sel_hi:[1,0]
	v_pk_mul_f32 v[50:51], v[58:59], v[62:63]
	v_pk_mul_f32 v[46:47], v[46:47], v[162:163] op_sel_hi:[1,0]
	v_pk_mul_f32 v[58:59], v[48:49], v[50:51]
	v_cvt_pk_bf16_f32 v48, v52, v53
	v_mad_i64_i32 v[52:53], s[0:1], v152, s59, v[112:113]
	v_cvt_pk_bf16_f32 v49, v54, v55
	v_cvt_pk_bf16_f32 v50, v56, v57
	v_cvt_pk_bf16_f32 v51, v58, v59
	v_lshl_add_u64 v[52:53], v[52:53], 0, v[114:115]
	v_mul_f32_e32 v54, 0xbfb8aa3b, v44
	global_store_dwordx4 v[52:53], v[48:51], off
	v_exp_f32_e32 v54, v54
	v_pk_mul_f32 v[36:37], v[36:37], v[162:163] op_sel_hi:[1,0]
	v_mul_f32_e32 v48, 0xbfb8aa3b, v45
	v_exp_f32_e32 v49, v48
	v_mul_f32_e32 v50, 0xbfb8aa3b, v46
	v_mul_f32_e32 v51, 0xbfb8aa3b, v47
	v_exp_f32_e32 v50, v50
	v_exp_f32_e32 v51, v51
	v_add_f32_e32 v48, 1.0, v54
	v_add_f32_e32 v49, 1.0, v49
	v_rcp_f32_e32 v48, v48
	v_rcp_f32_e32 v49, v49
	v_add_f32_e32 v50, 1.0, v50
	v_add_f32_e32 v51, 1.0, v51
	v_rcp_f32_e32 v50, v50
	v_rcp_f32_e32 v51, v51
	v_pk_mul_f32 v[44:45], v[44:45], v[48:49]
	v_pk_mul_f32 v[40:41], v[40:41], v[162:163] op_sel_hi:[1,0]
	v_pk_mul_f32 v[36:37], v[36:37], v[44:45]
	v_pk_mul_f32 v[44:45], v[46:47], v[50:51]
	v_mul_f32_e32 v46, 0xbfb8aa3b, v40
	v_exp_f32_e32 v46, v46
	v_pk_mul_f32 v[38:39], v[38:39], v[162:163] op_sel_hi:[1,0]
	v_pk_mul_f32 v[42:43], v[42:43], v[162:163] op_sel_hi:[1,0]
	v_pk_mul_f32 v[38:39], v[38:39], v[44:45]
	v_mul_f32_e32 v44, 0xbfb8aa3b, v41
	v_exp_f32_e32 v45, v44
	v_add_f32_e32 v44, 1.0, v46
	v_mul_f32_e32 v46, 0xbfb8aa3b, v42
	v_mul_f32_e32 v47, 0xbfb8aa3b, v43
	v_exp_f32_e32 v46, v46
	v_exp_f32_e32 v47, v47
	v_add_f32_e32 v45, 1.0, v45
	v_rcp_f32_e32 v44, v44
	v_rcp_f32_e32 v45, v45
	v_add_f32_e32 v46, 1.0, v46
	v_add_f32_e32 v47, 1.0, v47
	v_rcp_f32_e32 v46, v46
	v_rcp_f32_e32 v47, v47
	v_pk_mul_f32 v[32:33], v[32:33], v[162:163] op_sel_hi:[1,0]
	v_pk_mul_f32 v[40:41], v[40:41], v[44:45]
	v_pk_mul_f32 v[28:29], v[28:29], v[158:159] op_sel_hi:[1,0]
	v_pk_mul_f32 v[40:41], v[32:33], v[40:41]
	v_pk_mul_f32 v[32:33], v[34:35], v[162:163] op_sel_hi:[1,0]
	v_pk_mul_f32 v[34:35], v[42:43], v[46:47]
	v_pk_mul_f32 v[30:31], v[30:31], v[158:159] op_sel_hi:[1,0]
	v_pk_mul_f32 v[42:43], v[32:33], v[34:35]
	v_cvt_pk_bf16_f32 v32, v36, v37
	v_mad_i64_i32 v[36:37], s[0:1], v150, s59, v[112:113]
	v_cvt_pk_bf16_f32 v33, v38, v39
	v_cvt_pk_bf16_f32 v34, v40, v41
	v_cvt_pk_bf16_f32 v35, v42, v43
	v_lshl_add_u64 v[36:37], v[36:37], 0, v[114:115]
	v_mul_f32_e32 v38, 0xbfb8aa3b, v28
	global_store_dwordx4 v[36:37], v[32:35], off
	v_exp_f32_e32 v38, v38
	v_pk_mul_f32 v[20:21], v[20:21], v[158:159] op_sel_hi:[1,0]
	v_mul_f32_e32 v32, 0xbfb8aa3b, v29
	v_exp_f32_e32 v33, v32
	v_mul_f32_e32 v34, 0xbfb8aa3b, v30
	v_mul_f32_e32 v35, 0xbfb8aa3b, v31
	v_exp_f32_e32 v34, v34
	v_exp_f32_e32 v35, v35
	v_add_f32_e32 v32, 1.0, v38
	v_add_f32_e32 v33, 1.0, v33
	v_rcp_f32_e32 v32, v32
	v_rcp_f32_e32 v33, v33
	v_add_f32_e32 v34, 1.0, v34
	v_add_f32_e32 v35, 1.0, v35
	v_rcp_f32_e32 v34, v34
	v_rcp_f32_e32 v35, v35
	v_pk_mul_f32 v[28:29], v[28:29], v[32:33]
	v_pk_mul_f32 v[24:25], v[24:25], v[158:159] op_sel_hi:[1,0]
	v_pk_mul_f32 v[20:21], v[20:21], v[28:29]
	v_pk_mul_f32 v[28:29], v[30:31], v[34:35]
	v_mul_f32_e32 v30, 0xbfb8aa3b, v24
	v_exp_f32_e32 v30, v30
	v_pk_mul_f32 v[22:23], v[22:23], v[158:159] op_sel_hi:[1,0]
	v_pk_mul_f32 v[26:27], v[26:27], v[158:159] op_sel_hi:[1,0]
	v_pk_mul_f32 v[22:23], v[22:23], v[28:29]
	v_mul_f32_e32 v28, 0xbfb8aa3b, v25
	v_exp_f32_e32 v29, v28
	v_add_f32_e32 v28, 1.0, v30
	v_mul_f32_e32 v30, 0xbfb8aa3b, v26
	v_mul_f32_e32 v31, 0xbfb8aa3b, v27
	v_exp_f32_e32 v30, v30
	v_exp_f32_e32 v31, v31
	v_add_f32_e32 v29, 1.0, v29
	v_rcp_f32_e32 v28, v28
	v_rcp_f32_e32 v29, v29
	v_add_f32_e32 v30, 1.0, v30
	v_add_f32_e32 v31, 1.0, v31
	v_rcp_f32_e32 v30, v30
	v_rcp_f32_e32 v31, v31
	v_pk_mul_f32 v[16:17], v[16:17], v[158:159] op_sel_hi:[1,0]
	v_pk_mul_f32 v[24:25], v[24:25], v[28:29]
	v_pk_mul_f32 v[12:13], v[12:13], v[154:155] op_sel_hi:[1,0]
	v_pk_mul_f32 v[24:25], v[16:17], v[24:25]
	v_pk_mul_f32 v[16:17], v[18:19], v[158:159] op_sel_hi:[1,0]
	v_pk_mul_f32 v[18:19], v[26:27], v[30:31]
	v_pk_mul_f32 v[14:15], v[14:15], v[154:155] op_sel_hi:[1,0]
	v_pk_mul_f32 v[26:27], v[16:17], v[18:19]
	v_cvt_pk_bf16_f32 v16, v20, v21
	v_mad_i64_i32 v[20:21], s[0:1], v148, s59, v[112:113]
	v_cvt_pk_bf16_f32 v17, v22, v23
	v_cvt_pk_bf16_f32 v18, v24, v25
	v_cvt_pk_bf16_f32 v19, v26, v27
	v_lshl_add_u64 v[20:21], v[20:21], 0, v[114:115]
	v_mul_f32_e32 v22, 0xbfb8aa3b, v12
	global_store_dwordx4 v[20:21], v[16:19], off
	v_exp_f32_e32 v22, v22
	v_pk_mul_f32 v[4:5], v[4:5], v[154:155] op_sel_hi:[1,0]
	v_mul_f32_e32 v16, 0xbfb8aa3b, v13
	v_exp_f32_e32 v17, v16
	v_mul_f32_e32 v18, 0xbfb8aa3b, v14
	v_mul_f32_e32 v19, 0xbfb8aa3b, v15
	v_exp_f32_e32 v18, v18
	v_exp_f32_e32 v19, v19
	v_add_f32_e32 v16, 1.0, v22
	v_add_f32_e32 v17, 1.0, v17
	v_rcp_f32_e32 v16, v16
	v_rcp_f32_e32 v17, v17
	v_add_f32_e32 v18, 1.0, v18
	v_add_f32_e32 v19, 1.0, v19
	v_rcp_f32_e32 v18, v18
	v_rcp_f32_e32 v19, v19
	v_pk_mul_f32 v[12:13], v[12:13], v[16:17]
	v_pk_mul_f32 v[8:9], v[8:9], v[154:155] op_sel_hi:[1,0]
	v_pk_mul_f32 v[4:5], v[4:5], v[12:13]
	v_pk_mul_f32 v[12:13], v[14:15], v[18:19]
	v_mul_f32_e32 v14, 0xbfb8aa3b, v8
	v_exp_f32_e32 v14, v14
	v_pk_mul_f32 v[6:7], v[6:7], v[154:155] op_sel_hi:[1,0]
	v_pk_mul_f32 v[10:11], v[10:11], v[154:155] op_sel_hi:[1,0]
	v_pk_mul_f32 v[6:7], v[6:7], v[12:13]
	v_mul_f32_e32 v12, 0xbfb8aa3b, v9
	v_exp_f32_e32 v13, v12
	v_add_f32_e32 v12, 1.0, v14
	v_mul_f32_e32 v14, 0xbfb8aa3b, v10
	v_mul_f32_e32 v15, 0xbfb8aa3b, v11
	v_exp_f32_e32 v14, v14
	v_exp_f32_e32 v15, v15
	v_add_f32_e32 v13, 1.0, v13
	v_rcp_f32_e32 v12, v12
	v_rcp_f32_e32 v13, v13
	v_add_f32_e32 v14, 1.0, v14
	v_add_f32_e32 v15, 1.0, v15
	v_rcp_f32_e32 v14, v14
	v_rcp_f32_e32 v15, v15
	v_pk_mul_f32 v[0:1], v[0:1], v[154:155] op_sel_hi:[1,0]
	v_pk_mul_f32 v[8:9], v[8:9], v[12:13]
	s_and_b64 vcc, exec, s[2:3]
	v_pk_mul_f32 v[8:9], v[0:1], v[8:9]
	v_pk_mul_f32 v[0:1], v[2:3], v[154:155] op_sel_hi:[1,0]
	v_pk_mul_f32 v[2:3], v[10:11], v[14:15]
	s_mov_b32 s5, s12
	v_pk_mul_f32 v[10:11], v[0:1], v[2:3]
	v_cvt_pk_bf16_f32 v0, v4, v5
	v_mad_i64_i32 v[4:5], s[0:1], v146, s59, v[112:113]
	v_cvt_pk_bf16_f32 v1, v6, v7
	v_cvt_pk_bf16_f32 v2, v8, v9
	v_cvt_pk_bf16_f32 v3, v10, v11
	v_lshl_add_u64 v[4:5], v[4:5], 0, v[114:115]
	s_mov_b32 s4, s36
	s_mov_b64 s[42:43], s[40:41]
	s_mov_b64 s[44:45], s[38:39]
	global_store_dwordx4 v[4:5], v[0:3], off
	s_waitcnt vmcnt(8)
	v_xor_b32_e32 v184, 16, v177
	v_xor_b32_e32 v185, 32, v177
	v_lshlrev_b32_e32 v184, 2, v184
	v_lshlrev_b32_e32 v185, 2, v185
	v_mov_b32_e32 v190, s10
	v_pk_add_f32 v[216:217], v[216:217], v[218:219]
	v_pk_add_f32 v[220:221], v[220:221], v[222:223]
	v_pk_add_f32 v[224:225], v[224:225], v[226:227]
	v_pk_add_f32 v[196:197], v[196:197], v[198:199]
	v_pk_add_f32 v[200:201], v[200:201], v[202:203]
	v_pk_add_f32 v[204:205], v[204:205], v[206:207]
	v_pk_add_f32 v[208:209], v[208:209], v[210:211]
	v_pk_add_f32 v[212:213], v[212:213], v[214:215]
	v_add_f32_e32 v216, v216, v217
	v_add_f32_e32 v220, v220, v221
	v_add_f32_e32 v224, v224, v225
	v_add_f32_e32 v196, v196, v197
	v_add_f32_e32 v200, v200, v201
	v_add_f32_e32 v204, v204, v205
	v_add_f32_e32 v208, v208, v209
	v_add_f32_e32 v212, v212, v213
	ds_bpermute_b32 v218, v184, v216
	ds_bpermute_b32 v219, v184, v220
	ds_bpermute_b32 v222, v184, v224
	ds_bpermute_b32 v223, v184, v196
	ds_bpermute_b32 v226, v184, v200
	ds_bpermute_b32 v227, v184, v204
	ds_bpermute_b32 v198, v184, v208
	ds_bpermute_b32 v199, v184, v212
	s_waitcnt lgkmcnt(0)
	v_add_f32_e32 v216, v216, v218
	v_add_f32_e32 v220, v220, v219
	v_add_f32_e32 v224, v224, v222
	v_add_f32_e32 v196, v196, v223
	v_add_f32_e32 v200, v200, v226
	v_add_f32_e32 v204, v204, v227
	v_add_f32_e32 v208, v208, v198
	v_add_f32_e32 v212, v212, v199
	ds_bpermute_b32 v218, v185, v216
	ds_bpermute_b32 v219, v185, v220
	ds_bpermute_b32 v222, v185, v224
	ds_bpermute_b32 v223, v185, v196
	ds_bpermute_b32 v226, v185, v200
	ds_bpermute_b32 v227, v185, v204
	ds_bpermute_b32 v198, v185, v208
	ds_bpermute_b32 v199, v185, v212
	s_waitcnt lgkmcnt(0)
	v_add_f32_e32 v216, v216, v218
	v_add_f32_e32 v220, v220, v219
	v_add_f32_e32 v224, v224, v222
	v_add_f32_e32 v196, v196, v223
	v_add_f32_e32 v200, v200, v226
	v_add_f32_e32 v204, v204, v227
	v_add_f32_e32 v208, v208, v198
	v_add_f32_e32 v212, v212, v199
	v_fma_f32 v216, v216, s8, v190
	v_fma_f32 v220, v220, s8, v190
	v_fma_f32 v224, v224, s8, v190
	v_fma_f32 v196, v196, s8, v190
	v_fma_f32 v200, v200, s8, v190
	v_fma_f32 v204, v204, s8, v190
	v_fma_f32 v208, v208, s8, v190
	v_fma_f32 v212, v212, s8, v190
	v_rsq_f32_e32 v240, v216
	v_rsq_f32_e32 v176, v220
	v_rsq_f32_e32 v174, v224
	v_rsq_f32_e32 v170, v196
	v_rsq_f32_e32 v166, v200
	v_rsq_f32_e32 v162, v204
	v_rsq_f32_e32 v158, v208
	v_rsq_f32_e32 v241, v212
	s_and_b64 vcc, exec, s[2:3]
	s_mov_b32 s5, s12
	s_mov_b32 s4, s36
	s_cbranch_vccz .LBB0_1090
	s_waitcnt vmcnt(0)
	s_cmpk_gt_u32 s9, 0xff
	s_cbranch_scc1 .LBB0_1097
	s_barrier
